# LayerNorm: one rsqrtf denormal guard (argument var+1e-5, always normal) removed with the same peephole
# baseline (speedup 1.0000x reference)
; DI float bflo(unsigned w) { return __uint_as_float(w << 16); }
; DI float bfhi(unsigned w) { return __uint_as_float(w & 0xffff0000u); }
; DI float wave_sum(float v) { v = row16_sum(v); return (rdlane(v, 0) + rdlane(v, 16)) + (rdlane(v, 32) + rdlane(v, 48)); }
; DI void phase_ln(const bf16_t* vin, float* xf, bf16_t* xb, const float* g, const float* b, bool write_f32) {
;     ...
;     for (int r0 = blockIdx.x * 8 + wave; r0 < T_; r0 += nw * R) {
;         f32x4 v[R][4];
; #pragma unroll
;         for (int k = 0; k < R; ++k) {
;             const bf16_t* row = vin + (size_t)(r0 + k * nw) * D_;
; #pragma unroll
;             for (int i = 0; i < 4; ++i) { const u32x2 w = *(const u32x2*)(row + i * 256 + lane * 4); v[k][i] = (f32x4){bflo(w.x), bfhi(w.x), bflo(w.y), bfhi(w.y)}; }
;         }
; #pragma unroll
;         for (int k = 0; k < R; ++k) {
;             float s = 0.f;
; #pragma unroll
;             for (int i = 0; i < 4; ++i) s += (v[k][i][0] + v[k][i][1]) + (v[k][i][2] + v[k][i][3]);
;             const float mean = wave_sum(s) * (1.0f / 1024.0f);
;             float q = 0.f;
; #pragma unroll
;             for (int i = 0; i < 4; ++i) { const f32x4 d = v[k][i] - mean; q += (d[0] * d[0] + d[1] * d[1]) + (d[2] * d[2] + d[3] * d[3]); }
.Lln_nopf:
	v_lshl_add_u64 v[46:47], v[44:45], 0, v[136:137]
	v_mov_b64_e32 v[110:111], v[208:209]
	v_mov_b64_e32 v[112:113], v[210:211]
	v_mov_b64_e32 v[48:49], v[212:213]
	s_mul_i32 s0, s50, 24
	v_mov_b64_e32 v[46:47], v[214:215]
	v_lshl_add_u64 v[126:127], v[38:39], 0, v[136:137]
	v_lshl_add_u64 v[38:39], v[38:39], 0, s[14:15]
	v_lshl_add_u64 v[44:45], v[44:45], 0, s[14:15]
	v_lshlrev_b32_e32 v119, 16, v111
	v_lshlrev_b32_e32 v118, 16, v110
	v_lshlrev_b32_e32 v104, 16, v48
	v_and_b32_e32 v105, 0xffff0000, v48
	v_lshlrev_b32_e32 v103, 16, v46
	v_and_b32_e32 v99, 0xffff0000, v46
	v_lshlrev_b32_e32 v101, 16, v47
	v_and_b32_e32 v97, 0xffff0000, v47
	v_lshl_add_u64 v[46:47], v[40:41], 0, v[136:137]
	v_lshlrev_b32_e32 v106, 16, v49
	v_and_b32_e32 v107, 0xffff0000, v49
	v_mov_b64_e32 v[108:109], v[216:217]
	v_mov_b64_e32 v[94:95], v[218:219]
	v_mov_b64_e32 v[48:49], v[220:221]
	v_and_b32_e32 v111, 0xffff0000, v111
	v_mov_b64_e32 v[46:47], v[222:223]
	v_and_b32_e32 v110, 0xffff0000, v110
	v_pk_add_f32 v[114:115], v[118:119], v[110:111]
	v_lshlrev_b32_e32 v117, 16, v113
	v_lshlrev_b32_e32 v116, 16, v112
	v_and_b32_e32 v113, 0xffff0000, v113
	v_and_b32_e32 v112, 0xffff0000, v112
	v_add_f32_e32 v33, v114, v115
	v_pk_add_f32 v[114:115], v[116:117], v[112:113]
	v_add_f32_e32 v102, 0, v33
	v_pk_add_f32 v[114:115], v[114:115], v[114:115] op_sel:[0,1] op_sel_hi:[1,0]
	v_add_f32_e32 v100, v104, v105
	v_add_f32_e32 v96, v106, v107
	v_mov_b32_e32 v115, v99
	v_pk_add_f32 v[114:115], v[102:103], v[114:115]
	v_pk_add_f32 v[120:121], v[100:101], v[96:97]
	v_lshl_add_u64 v[40:41], v[40:41], 0, s[14:15]
	v_pk_add_f32 v[114:115], v[114:115], v[120:121]
	v_lshlrev_b32_e32 v86, 16, v48
	v_and_b32_e32 v87, 0xffff0000, v48
	v_lshlrev_b32_e32 v85, 16, v46
	v_and_b32_e32 v81, 0xffff0000, v46
	v_add_u32_e32 v46, s34, v32
	v_lshlrev_b32_e32 v83, 16, v47
	v_and_b32_e32 v79, 0xffff0000, v47
	v_ashrrev_i32_e32 v47, 31, v46
	v_lshlrev_b64 v[72:73], 11, v[46:47]
	v_lshl_add_u64 v[46:47], v[34:35], 0, v[72:73]
	v_lshlrev_b32_e32 v88, 16, v49
	v_and_b32_e32 v89, 0xffff0000, v49
	v_mov_b64_e32 v[92:93], v[224:225]
	v_mov_b64_e32 v[90:91], v[226:227]
	v_mov_b64_e32 v[48:49], v[228:229]
	v_add_f32_e32 v33, v114, v115
	v_mov_b64_e32 v[46:47], v[230:231]
	v_add_f32_e32 v82, v86, v87
	v_add_f32_dpp v33, v33, v33 quad_perm:[1,0,3,2] row_mask:0xf bank_mask:0xf bound_ctrl:1
	v_add_f32_e32 v78, v88, v89
	v_pk_add_f32 v[128:129], v[82:83], v[78:79]
	v_add_f32_dpp v33, v33, v33 quad_perm:[2,3,0,1] row_mask:0xf bank_mask:0xf bound_ctrl:1
	v_lshl_add_u64 v[72:73], v[36:37], 0, v[72:73]
	v_lshlrev_b32_e32 v68, 16, v48
	v_and_b32_e32 v69, 0xffff0000, v48
	v_lshlrev_b32_e32 v67, 16, v46
	v_and_b32_e32 v63, 0xffff0000, v46
	v_add_u32_e32 v46, s0, v32
	v_lshlrev_b32_e32 v65, 16, v47
	v_and_b32_e32 v61, 0xffff0000, v47
	v_ashrrev_i32_e32 v47, 31, v46
	v_lshlrev_b64 v[58:59], 11, v[46:47]
	v_lshl_add_u64 v[46:47], v[34:35], 0, v[58:59]
	v_lshlrev_b32_e32 v70, 16, v49
	v_and_b32_e32 v71, 0xffff0000, v49
	v_mov_b64_e32 v[76:77], v[232:233]
	v_mov_b64_e32 v[74:75], v[234:235]
	v_mov_b64_e32 v[48:49], v[236:237]
	v_add_f32_dpp v33, v33, v33 row_half_mirror row_mask:0xf bank_mask:0xf bound_ctrl:1
	v_mov_b64_e32 v[46:47], v[238:239]
	v_add_f32_e32 v64, v68, v69
	v_add_f32_dpp v33, v33, v33 row_mirror row_mask:0xf bank_mask:0xf bound_ctrl:1
	v_add_f32_e32 v60, v70, v71
	v_readlane_b32 s8, v33, 16
	v_readlane_b32 s9, v33, 48
	v_readlane_b32 s0, v33, 0
	v_readlane_b32 s1, v33, 32
	v_mov_b32_e32 v114, s8
	v_mov_b32_e32 v115, s9
	v_pk_add_f32 v[114:115], s[0:1], v[114:115]
	v_lshl_add_u64 v[58:59], v[36:37], 0, v[58:59]
	v_add_f32_e32 v33, v114, v115
	v_fmac_f32_e32 v110, 0xba800000, v33
	v_fmac_f32_e32 v111, 0xba800000, v33
	v_fmac_f32_e32 v119, 0xba800000, v33
	v_fmac_f32_e32 v118, 0xba800000, v33
	v_mov_b32_e32 v122, v119
	v_mov_b32_e32 v123, v111
	v_mov_b32_e32 v119, v110
	v_pk_mul_f32 v[114:115], v[122:123], v[122:123]
	v_pk_mul_f32 v[110:111], v[118:119], v[118:119]
	v_fmac_f32_e32 v112, 0xba800000, v33
	v_pk_mov_b32 v[120:121], v[110:111], v[114:115] op_sel:[1,0]
	v_mov_b32_e32 v111, v115
	v_fmac_f32_e32 v113, 0xba800000, v33
	v_fmac_f32_e32 v117, 0xba800000, v33
	v_pk_add_f32 v[110:111], v[120:121], v[110:111]
	v_fmac_f32_e32 v116, 0xba800000, v33
	v_mov_b32_e32 v120, v117
	v_mov_b32_e32 v121, v113
	v_mov_b32_e32 v117, v112
	v_pk_mul_f32 v[114:115], v[120:121], v[120:121]
	v_pk_mul_f32 v[112:113], v[116:117], v[116:117]
	v_fmac_f32_e32 v104, 0xba800000, v33
	v_pk_mov_b32 v[124:125], v[112:113], v[114:115] op_sel:[1,0]
	v_mov_b32_e32 v113, v115
	v_fmac_f32_e32 v105, 0xba800000, v33
	v_fmac_f32_e32 v106, 0xba800000, v33
	v_pk_add_f32 v[112:113], v[124:125], v[112:113]
	v_fmac_f32_e32 v107, 0xba800000, v33
	v_pk_add_f32 v[110:111], v[110:111], v[110:111] op_sel_hi:[0,1]
	v_pk_add_f32 v[112:113], v[112:113], v[112:113] op_sel_hi:[0,1]
	v_fmac_f32_e32 v97, 0xba800000, v33
	v_fmac_f32_e32 v101, 0xba800000, v33
	v_fmac_f32_e32 v99, 0xba800000, v33
	v_fmac_f32_e32 v103, 0xba800000, v33
	v_mul_f32_e32 v110, v101, v101
	v_mul_f32_e32 v112, v97, v97
	v_pk_add_f32 v[110:111], v[110:111], v[112:113]
	v_and_b32_e32 v113, 0xffff0000, v109
	v_and_b32_e32 v112, 0xffff0000, v108
	v_mov_b32_e32 v98, v103
	v_mov_b32_e32 v96, v101
	v_add_u32_e32 v32, s54, v32
	v_lshlrev_b32_e32 v56, 16, v49
	v_and_b32_e32 v57, 0xffff0000, v49
	v_lshlrev_b32_e32 v53, 16, v46
	v_and_b32_e32 v49, 0xffff0000, v46
	v_lshlrev_b32_e32 v51, 16, v47
	v_and_b32_e32 v47, 0xffff0000, v47
	v_mul_f32_e32 v46, v104, v104
	v_pk_fma_f32 v[114:115], v[104:105], v[104:105], v[46:47] op_sel_hi:[1,1,0]
	v_mul_f32_e32 v46, v106, v106
; DI unsigned pk2(float lo, float hi) { return f2bf(lo) | (f2bf(hi) << 16); }
; DI float wave_sum(float v) { v = row16_sum(v); return (rdlane(v, 0) + rdlane(v, 16)) + (rdlane(v, 32) + rdlane(v, 48)); }
; DI void phase_ln(const bf16_t* vin, float* xf, bf16_t* xb, const float* g, const float* b, bool write_f32) {
;     ...
;         for (int k = 0; k < R; ++k) {
;             float s = 0.f;
; #pragma unroll
;             for (int i = 0; i < 4; ++i) s += (v[k][i][0] + v[k][i][1]) + (v[k][i][2] + v[k][i][3]);
;             const float mean = wave_sum(s) * (1.0f / 1024.0f);
;             float q = 0.f;
; #pragma unroll
;             for (int i = 0; i < 4; ++i) { const f32x4 d = v[k][i] - mean; q += (d[0] * d[0] + d[1] * d[1]) + (d[2] * d[2] + d[3] * d[3]); }
;             const float rstd = rsqrtf(wave_sum(q) * (1.0f / 1024.0f) + 1e-5f);
;             float* row = xf + (size_t)(r0 + k * nw) * D_;
;             bf16_t* rb = xb + (size_t)(r0 + k * nw) * D_;
; #pragma unroll
;             for (int i = 0; i < 4; ++i) {
;                 const f32x4 o = (v[k][i] - mean) * rstd * gv[i] + bv[i];
;                 if (write_f32) *(f32x4*)(row + i * 256 + lane * 4) = o;
;                 u32x2 w; w.x = pk2(o[0], o[1]); w.y = pk2(o[2], o[3]);
;                 *(u32x2*)(rb + i * 256 + lane * 4) = w;
	v_pk_fma_f32 v[124:125], v[106:107], v[106:107], v[46:47] op_sel_hi:[1,1,0]
	v_mul_f32_e32 v114, v103, v103
	v_mul_f32_e32 v124, v99, v99
	v_pk_add_f32 v[114:115], v[114:115], v[124:125]
	v_lshlrev_b32_e32 v54, 16, v48
	v_pk_add_f32 v[110:111], v[114:115], v[110:111]
	v_and_b32_e32 v55, 0xffff0000, v48
	v_add_f32_e32 v33, v110, v111
	v_add_f32_e32 v50, v54, v55
	s_nop 0
	v_add_f32_dpp v33, v33, v33 quad_perm:[1,0,3,2] row_mask:0xf bank_mask:0xf bound_ctrl:1
	s_nop 1
	v_add_f32_dpp v33, v33, v33 quad_perm:[2,3,0,1] row_mask:0xf bank_mask:0xf bound_ctrl:1
	s_nop 1
	v_add_f32_dpp v33, v33, v33 row_half_mirror row_mask:0xf bank_mask:0xf bound_ctrl:1
	s_nop 1
	v_add_f32_dpp v33, v33, v33 row_mirror row_mask:0xf bank_mask:0xf bound_ctrl:1
	s_nop 0
	v_readlane_b32 s8, v33, 16
	v_readlane_b32 s9, v33, 48
	v_readlane_b32 s0, v33, 0
	v_readlane_b32 s1, v33, 32
	v_mov_b32_e32 v110, s8
	v_mov_b32_e32 v111, s9
	v_pk_add_f32 v[124:125], s[0:1], v[110:111]
	v_lshlrev_b32_e32 v111, 16, v109
	v_lshlrev_b32_e32 v110, 16, v108
	v_pk_add_f32 v[108:109], v[110:111], v[112:113]
	s_nop 0
	v_add_f32_e32 v33, v108, v109
	v_lshlrev_b32_e32 v109, 16, v95
	v_lshlrev_b32_e32 v108, 16, v94
	v_and_b32_e32 v95, 0xffff0000, v95
	v_and_b32_e32 v94, 0xffff0000, v94
	v_pk_add_f32 v[114:115], v[108:109], v[94:95]
	v_add_f32_e32 v84, 0, v33
	v_pk_add_f32 v[114:115], v[114:115], v[114:115] op_sel:[0,1] op_sel_hi:[1,0]
	s_nop 0
	v_mov_b32_e32 v115, v81
	v_pk_add_f32 v[114:115], v[84:85], v[114:115]
	v_and_b32_e32 v84, 0xffff0000, v90
	v_pk_add_f32 v[114:115], v[114:115], v[128:129]
	s_nop 0
	v_add_f32_e32 v33, v114, v115
	s_nop 1
	v_add_f32_dpp v33, v33, v33 quad_perm:[1,0,3,2] row_mask:0xf bank_mask:0xf bound_ctrl:1
	s_nop 1
	v_add_f32_dpp v33, v33, v33 quad_perm:[2,3,0,1] row_mask:0xf bank_mask:0xf bound_ctrl:1
	s_nop 1
	v_add_f32_dpp v33, v33, v33 row_half_mirror row_mask:0xf bank_mask:0xf bound_ctrl:1
	s_nop 1
	v_add_f32_dpp v33, v33, v33 row_mirror row_mask:0xf bank_mask:0xf bound_ctrl:1
	s_nop 0
	v_readlane_b32 s8, v33, 16
	v_readlane_b32 s9, v33, 48
	v_readlane_b32 s0, v33, 0
	v_readlane_b32 s1, v33, 32
	v_mov_b32_e32 v114, s8
	v_mov_b32_e32 v115, s9
	v_pk_add_f32 v[114:115], s[0:1], v[114:115]
	s_nop 0
	v_add_f32_e32 v33, v114, v115
	v_fmac_f32_e32 v112, 0xba800000, v33
	v_fmac_f32_e32 v113, 0xba800000, v33
	v_fmac_f32_e32 v111, 0xba800000, v33
	v_fmac_f32_e32 v110, 0xba800000, v33
	v_mov_b32_e32 v114, v111
	v_mov_b32_e32 v115, v113
	v_mov_b32_e32 v111, v112
	v_pk_mul_f32 v[128:129], v[114:115], v[114:115]
	v_pk_mul_f32 v[112:113], v[110:111], v[110:111]
	v_fmac_f32_e32 v94, 0xba800000, v33
	v_pk_mov_b32 v[130:131], v[112:113], v[128:129] op_sel:[1,0]
	v_mov_b32_e32 v113, v129
	v_pk_add_f32 v[112:113], v[130:131], v[112:113]
	v_fmac_f32_e32 v95, 0xba800000, v33
	v_fmac_f32_e32 v109, 0xba800000, v33
	v_pk_add_f32 v[128:129], v[112:113], v[112:113] op_sel_hi:[0,1]
	v_fmac_f32_e32 v108, 0xba800000, v33
	v_mov_b32_e32 v112, v109
	v_mov_b32_e32 v113, v95
	v_mov_b32_e32 v109, v94
	v_pk_mul_f32 v[130:131], v[112:113], v[112:113]
	v_pk_mul_f32 v[94:95], v[108:109], v[108:109]
	v_fmac_f32_e32 v86, 0xba800000, v33
	v_pk_mov_b32 v[132:133], v[94:95], v[130:131] op_sel:[1,0]
	v_mov_b32_e32 v95, v131
	v_fmac_f32_e32 v87, 0xba800000, v33
	v_fmac_f32_e32 v88, 0xba800000, v33
	v_mul_f32_e32 v46, v86, v86
	v_pk_add_f32 v[94:95], v[132:133], v[94:95]
	v_fmac_f32_e32 v89, 0xba800000, v33
	v_pk_fma_f32 v[130:131], v[86:87], v[86:87], v[46:47] op_sel_hi:[1,1,0]
	v_mul_f32_e32 v46, v88, v88
	v_pk_add_f32 v[94:95], v[94:95], v[94:95] op_sel_hi:[0,1]
	v_pk_fma_f32 v[132:133], v[88:89], v[88:89], v[46:47] op_sel_hi:[1,1,0]
	v_fmac_f32_e32 v79, 0xba800000, v33
	v_fmac_f32_e32 v83, 0xba800000, v33
	v_fmac_f32_e32 v81, 0xba800000, v33
	v_fmac_f32_e32 v85, 0xba800000, v33
	v_mul_f32_e32 v130, v85, v85
	v_mul_f32_e32 v132, v81, v81
	v_mul_f32_e32 v128, v83, v83
	v_mul_f32_e32 v94, v79, v79
	v_pk_add_f32 v[130:131], v[130:131], v[132:133]
	v_pk_add_f32 v[94:95], v[128:129], v[94:95]
	v_mov_b32_e32 v129, v124
	v_pk_add_f32 v[94:95], v[130:131], v[94:95]
	v_mov_b32_e32 v80, v85
	v_add_f32_e32 v33, v94, v95
	v_mov_b32_e32 v78, v83
	v_and_b32_e32 v85, 0xffff0000, v91
	v_add_f32_dpp v33, v33, v33 quad_perm:[1,0,3,2] row_mask:0xf bank_mask:0xf bound_ctrl:1
	s_nop 1
	v_add_f32_dpp v33, v33, v33 quad_perm:[2,3,0,1] row_mask:0xf bank_mask:0xf bound_ctrl:1
	s_nop 1
	v_add_f32_dpp v33, v33, v33 row_half_mirror row_mask:0xf bank_mask:0xf bound_ctrl:1
	s_nop 1
	v_add_f32_dpp v33, v33, v33 row_mirror row_mask:0xf bank_mask:0xf bound_ctrl:1
	s_nop 0
	v_readlane_b32 s8, v33, 16
	v_readlane_b32 s9, v33, 48
	v_readlane_b32 s0, v33, 0
	v_readlane_b32 s1, v33, 32
	v_mov_b32_e32 v94, s8
	v_mov_b32_e32 v95, s9
	v_pk_add_f32 v[94:95], s[0:1], v[94:95]
	s_mov_b32 s0, 0x3727c5ac
	v_mov_b32_e32 v128, v94
	v_mov_b32_e32 v124, v95
	v_pk_add_f32 v[124:125], v[128:129], v[124:125]
	v_mov_b64_e32 v[94:95], s[0:1]
	v_pk_fma_f32 v[124:125], v[124:125], s[18:19], v[94:95] op_sel_hi:[1,0,0]
	s_nop 0
	v_mul_f32_e32 v33, 0x4b800000, v125
	v_cmp_gt_f32_e64 s[0:1], s44, v125
	v_cmp_gt_f32_e32 vcc, s44, v124
	s_nop 0
	v_cndmask_b32_e64 v33, v125, v33, s[0:1]
	v_rsq_f32_e32 v33, v33
	s_nop 0
	v_mul_f32_e32 v46, 0x45800000, v33
	v_cndmask_b32_e64 v46, v33, v46, s[0:1]
	v_pk_mul_f32 v[118:119], v[118:119], v[46:47] op_sel_hi:[1,0]
	v_pk_mul_f32 v[122:123], v[122:123], v[46:47] op_sel_hi:[1,0]
	v_pk_fma_f32 v[118:119], v[0:1], v[118:119], v[8:9]
	v_pk_fma_f32 v[122:123], v[2:3], v[122:123], v[10:11]
	v_cvt_pk_bf16_f32 v118, v118, v119
	v_cvt_pk_bf16_f32 v33, v122, v122
	v_bfe_u32 v48, v123, 16, 1
	v_pk_mul_f32 v[116:117], v[116:117], v[46:47] op_sel_hi:[1,0]
; DI unsigned pk2(float lo, float hi) { return f2bf(lo) | (f2bf(hi) << 16); }
; DI float wave_sum(float v) { v = row16_sum(v); return (rdlane(v, 0) + rdlane(v, 16)) + (rdlane(v, 32) + rdlane(v, 48)); }
; DI void phase_ln(const bf16_t* vin, float* xf, bf16_t* xb, const float* g, const float* b, bool write_f32) {
;     ...
;         for (int k = 0; k < R; ++k) {
;             float s = 0.f;
; #pragma unroll
;             for (int i = 0; i < 4; ++i) s += (v[k][i][0] + v[k][i][1]) + (v[k][i][2] + v[k][i][3]);
;             const float mean = wave_sum(s) * (1.0f / 1024.0f);
;             float q = 0.f;
; #pragma unroll
;             for (int i = 0; i < 4; ++i) { const f32x4 d = v[k][i] - mean; q += (d[0] * d[0] + d[1] * d[1]) + (d[2] * d[2] + d[3] * d[3]); }
;             const float rstd = rsqrtf(wave_sum(q) * (1.0f / 1024.0f) + 1e-5f);
;             float* row = xf + (size_t)(r0 + k * nw) * D_;
;             bf16_t* rb = xb + (size_t)(r0 + k * nw) * D_;
; #pragma unroll
;             for (int i = 0; i < 4; ++i) {
;                 const f32x4 o = (v[k][i] - mean) * rstd * gv[i] + bv[i];
;                 if (write_f32) *(f32x4*)(row + i * 256 + lane * 4) = o;
;                 u32x2 w; w.x = pk2(o[0], o[1]); w.y = pk2(o[2], o[3]);
;                 *(u32x2*)(rb + i * 256 + lane * 4) = w;
	v_lshrrev_b32_e32 v33, 16, v33
	v_add3_u32 v48, v123, v48, s68
	v_add_co_u32_e64 v122, s[0:1], s16, v126
	v_pk_fma_f32 v[116:117], v[4:5], v[116:117], v[12:13]
	v_and_or_b32 v119, v48, s39, v33
	v_addc_co_u32_e64 v123, s[0:1], 0, v127, s[0:1]
	s_nop 0
	global_store_dwordx2 v[122:123], v[118:119], off
	v_pk_mul_f32 v[118:119], v[120:121], v[46:47] op_sel_hi:[1,0]
	s_nop 0
	s_nop 0
	v_pk_fma_f32 v[118:119], v[6:7], v[118:119], v[14:15]
	v_cvt_pk_bf16_f32 v116, v116, v117
	v_pk_mul_f32 v[104:105], v[104:105], v[46:47] op_sel_hi:[1,0]
	v_pk_fma_f32 v[104:105], v[16:17], v[104:105], v[24:25]
	v_cvt_pk_bf16_f32 v117, v118, v119
	v_pk_mul_f32 v[106:107], v[106:107], v[46:47] op_sel_hi:[1,0]
	v_pk_fma_f32 v[106:107], v[18:19], v[106:107], v[26:27]
	v_cvt_pk_bf16_f32 v104, v104, v105
	v_pk_mul_f32 v[98:99], v[98:99], v[46:47] op_sel_hi:[1,0]
	v_pk_fma_f32 v[98:99], v[20:21], v[98:99], v[28:29]
	v_cvt_pk_bf16_f32 v105, v106, v107
	v_pk_mul_f32 v[96:97], v[96:97], v[46:47] op_sel_hi:[1,0]
	v_pk_fma_f32 v[96:97], v[22:23], v[96:97], v[30:31]
	v_cvt_pk_bf16_f32 v98, v98, v99
	s_nop 0
	s_nop 0
	v_cvt_pk_bf16_f32 v99, v96, v97
	v_mul_f32_e32 v33, 0x4b800000, v124
	v_cndmask_b32_e32 v33, v124, v33, vcc
	v_rsq_f32_e32 v33, v33
	global_store_dwordx2 v[122:123], v[98:99], off offset:1536
	v_lshl_add_u64 v[96:97], v[42:43], 0, v[136:137]
	global_store_dwordx2 v[122:123], v[116:117], off offset:512
	v_mul_f32_e32 v46, 0x45800000, v33
	v_cndmask_b32_e32 v46, v33, v46, vcc
	v_pk_mul_f32 v[98:99], v[110:111], v[46:47] op_sel_hi:[1,0]
	v_pk_mul_f32 v[100:101], v[114:115], v[46:47] op_sel_hi:[1,0]
	v_pk_fma_f32 v[98:99], v[0:1], v[98:99], v[8:9]
	v_pk_fma_f32 v[100:101], v[2:3], v[100:101], v[10:11]
	v_cvt_pk_bf16_f32 v98, v98, v99
	s_nop 0
	s_nop 0
	s_nop 0
	s_nop 0
	v_add_co_u32_e32 v96, vcc, s16, v96
	v_cvt_pk_bf16_f32 v99, v100, v101
	s_nop 0
	v_addc_co_u32_e32 v97, vcc, 0, v97, vcc
	global_store_dwordx2 v[122:123], v[104:105], off offset:1024
	global_store_dwordx2 v[96:97], v[98:99], off
	v_pk_mul_f32 v[98:99], v[108:109], v[46:47] op_sel_hi:[1,0]
	v_pk_mul_f32 v[100:101], v[112:113], v[46:47] op_sel_hi:[1,0]
	v_pk_fma_f32 v[98:99], v[4:5], v[98:99], v[12:13]
	v_pk_fma_f32 v[100:101], v[6:7], v[100:101], v[14:15]
	v_cvt_pk_bf16_f32 v98, v98, v99
	v_pk_mul_f32 v[86:87], v[86:87], v[46:47] op_sel_hi:[1,0]
	v_pk_fma_f32 v[86:87], v[16:17], v[86:87], v[24:25]
	v_cvt_pk_bf16_f32 v99, v100, v101
	v_pk_mul_f32 v[88:89], v[88:89], v[46:47] op_sel_hi:[1,0]
	v_pk_fma_f32 v[88:89], v[18:19], v[88:89], v[26:27]
	v_cvt_pk_bf16_f32 v86, v86, v87
	v_pk_mul_f32 v[80:81], v[80:81], v[46:47] op_sel_hi:[1,0]
	v_pk_fma_f32 v[80:81], v[20:21], v[80:81], v[28:29]
	v_cvt_pk_bf16_f32 v87, v88, v89
	v_pk_mul_f32 v[78:79], v[78:79], v[46:47] op_sel_hi:[1,0]
	v_pk_fma_f32 v[78:79], v[22:23], v[78:79], v[30:31]
	v_cvt_pk_bf16_f32 v80, v80, v81
	s_nop 0
	s_nop 0
	s_nop 0
	v_cvt_pk_bf16_f32 v81, v78, v79
	global_store_dwordx2 v[96:97], v[80:81], off offset:1536
	v_lshlrev_b32_e32 v79, 16, v93
	v_lshlrev_b32_e32 v78, 16, v92
	v_and_b32_e32 v81, 0xffff0000, v93
	v_and_b32_e32 v80, 0xffff0000, v92
	v_pk_add_f32 v[82:83], v[78:79], v[80:81]
	global_store_dwordx2 v[96:97], v[86:87], off offset:1024
	v_add_f32_e32 v33, v82, v83
	v_lshlrev_b32_e32 v83, 16, v91
	v_lshlrev_b32_e32 v82, 16, v90
	v_pk_add_f32 v[86:87], v[82:83], v[84:85]
	v_add_f32_e32 v66, 0, v33
	v_pk_add_f32 v[86:87], v[86:87], v[86:87] op_sel:[0,1] op_sel_hi:[1,0]
	v_pk_add_f32 v[88:89], v[64:65], v[60:61]
	v_mov_b32_e32 v87, v63
	v_pk_add_f32 v[86:87], v[66:67], v[86:87]
	global_store_dwordx2 v[96:97], v[98:99], off offset:512
	v_pk_add_f32 v[86:87], v[86:87], v[88:89]
	v_lshl_add_u64 v[42:43], v[42:43], 0, s[14:15]
	v_add_f32_e32 v33, v86, v87
	s_nop 1
	v_add_f32_dpp v33, v33, v33 quad_perm:[1,0,3,2] row_mask:0xf bank_mask:0xf bound_ctrl:1
	s_nop 1
	v_add_f32_dpp v33, v33, v33 quad_perm:[2,3,0,1] row_mask:0xf bank_mask:0xf bound_ctrl:1
	s_nop 1
	v_add_f32_dpp v33, v33, v33 row_half_mirror row_mask:0xf bank_mask:0xf bound_ctrl:1
	s_nop 1
	v_add_f32_dpp v33, v33, v33 row_mirror row_mask:0xf bank_mask:0xf bound_ctrl:1
	s_nop 0
	v_readlane_b32 s8, v33, 16
	v_readlane_b32 s9, v33, 48
	v_readlane_b32 s0, v33, 0
	v_readlane_b32 s1, v33, 32
	v_mov_b32_e32 v86, s8
	v_mov_b32_e32 v87, s9
	v_pk_add_f32 v[86:87], s[0:1], v[86:87]
	s_nop 0
	v_add_f32_e32 v33, v86, v87
	v_fmac_f32_e32 v80, 0xba800000, v33
	v_fmac_f32_e32 v81, 0xba800000, v33
	v_fmac_f32_e32 v79, 0xba800000, v33
	v_fmac_f32_e32 v78, 0xba800000, v33
	v_mov_b32_e32 v86, v79
	v_mov_b32_e32 v87, v81
	v_mov_b32_e32 v79, v80
	v_pk_mul_f32 v[88:89], v[86:87], v[86:87]
	v_pk_mul_f32 v[80:81], v[78:79], v[78:79]
	v_fmac_f32_e32 v84, 0xba800000, v33
	v_fmac_f32_e32 v85, 0xba800000, v33
	v_fmac_f32_e32 v83, 0xba800000, v33
	v_pk_mov_b32 v[90:91], v[80:81], v[88:89] op_sel:[1,0]
	v_mov_b32_e32 v81, v89
	v_fmac_f32_e32 v82, 0xba800000, v33
	v_mov_b32_e32 v88, v83
	v_mov_b32_e32 v89, v85
	v_mov_b32_e32 v83, v84
	v_pk_add_f32 v[80:81], v[90:91], v[80:81]
	v_pk_mul_f32 v[90:91], v[88:89], v[88:89]
	v_pk_mul_f32 v[84:85], v[82:83], v[82:83]
	v_fmac_f32_e32 v68, 0xba800000, v33
	v_pk_mov_b32 v[92:93], v[84:85], v[90:91] op_sel:[1,0]
	v_mov_b32_e32 v85, v91
	v_fmac_f32_e32 v69, 0xba800000, v33
	v_fmac_f32_e32 v70, 0xba800000, v33
	v_mul_f32_e32 v46, v68, v68
	v_pk_add_f32 v[84:85], v[92:93], v[84:85]
	v_fmac_f32_e32 v71, 0xba800000, v33
	v_pk_fma_f32 v[90:91], v[68:69], v[68:69], v[46:47] op_sel_hi:[1,1,0]
	v_mul_f32_e32 v46, v70, v70
	v_pk_add_f32 v[80:81], v[80:81], v[80:81] op_sel_hi:[0,1]
	v_pk_add_f32 v[84:85], v[84:85], v[84:85] op_sel_hi:[0,1]
	v_pk_fma_f32 v[92:93], v[70:71], v[70:71], v[46:47] op_sel_hi:[1,1,0]
; DI float wave_sum(float v) { v = row16_sum(v); return (rdlane(v, 0) + rdlane(v, 16)) + (rdlane(v, 32) + rdlane(v, 48)); }
; DI void phase_ln(const bf16_t* vin, float* xf, bf16_t* xb, const float* g, const float* b, bool write_f32) {
;     ...
;         for (int k = 0; k < R; ++k) {
;             float s = 0.f;
; #pragma unroll
;             for (int i = 0; i < 4; ++i) s += (v[k][i][0] + v[k][i][1]) + (v[k][i][2] + v[k][i][3]);
;             const float mean = wave_sum(s) * (1.0f / 1024.0f);
;             float q = 0.f;
; #pragma unroll
;             for (int i = 0; i < 4; ++i) { const f32x4 d = v[k][i] - mean; q += (d[0] * d[0] + d[1] * d[1]) + (d[2] * d[2] + d[3] * d[3]); }
;             const float rstd = rsqrtf(wave_sum(q) * (1.0f / 1024.0f) + 1e-5f);
	v_fmac_f32_e32 v61, 0xba800000, v33
	v_fmac_f32_e32 v65, 0xba800000, v33
	v_fmac_f32_e32 v63, 0xba800000, v33
	v_fmac_f32_e32 v67, 0xba800000, v33
	v_mul_f32_e32 v90, v67, v67
	v_mul_f32_e32 v92, v63, v63
	v_mul_f32_e32 v80, v65, v65
	v_mul_f32_e32 v84, v61, v61
	v_pk_add_f32 v[90:91], v[90:91], v[92:93]
	v_pk_add_f32 v[80:81], v[80:81], v[84:85]
	v_lshlrev_b32_e32 v85, 16, v77
	v_pk_add_f32 v[80:81], v[90:91], v[80:81]
	v_lshlrev_b32_e32 v84, 16, v76
	v_add_f32_e32 v33, v80, v81
	v_and_b32_e32 v77, 0xffff0000, v77
	v_and_b32_e32 v76, 0xffff0000, v76
	v_add_f32_dpp v33, v33, v33 quad_perm:[1,0,3,2] row_mask:0xf bank_mask:0xf bound_ctrl:1
	v_pk_add_f32 v[90:91], v[84:85], v[76:77]
	v_add_f32_e32 v46, v56, v57
	v_add_f32_dpp v33, v33, v33 quad_perm:[2,3,0,1] row_mask:0xf bank_mask:0xf bound_ctrl:1
	v_pk_add_f32 v[96:97], v[50:51], v[46:47]
	v_mov_b32_e32 v62, v67
	v_add_f32_dpp v33, v33, v33 row_half_mirror row_mask:0xf bank_mask:0xf bound_ctrl:1
	v_mov_b32_e32 v60, v65
	s_nop 0
	v_add_f32_dpp v33, v33, v33 row_mirror row_mask:0xf bank_mask:0xf bound_ctrl:1
	s_nop 0
	v_readlane_b32 s0, v33, 0
	v_readlane_b32 s8, v33, 16
	v_readlane_b32 s1, v33, 32
	v_readlane_b32 s9, v33, 48
	v_add_f32_e32 v33, v90, v91
	v_lshlrev_b32_e32 v91, 16, v75
	v_lshlrev_b32_e32 v90, 16, v74
	v_and_b32_e32 v75, 0xffff0000, v75
	v_and_b32_e32 v74, 0xffff0000, v74
	v_pk_add_f32 v[92:93], v[90:91], v[74:75]
	v_add_f32_e32 v52, 0, v33
	v_pk_add_f32 v[92:93], v[92:93], v[92:93] op_sel:[0,1] op_sel_hi:[1,0]
	v_mov_b32_e32 v80, s8
	v_mov_b32_e32 v93, v49
	v_pk_add_f32 v[92:93], v[52:53], v[92:93]
	v_mov_b32_e32 v81, s9
	v_pk_add_f32 v[92:93], v[92:93], v[96:97]
	v_pk_add_f32 v[80:81], s[0:1], v[80:81]
	v_add_f32_e32 v33, v92, v93
	s_nop 1
	v_add_f32_dpp v33, v33, v33 quad_perm:[1,0,3,2] row_mask:0xf bank_mask:0xf bound_ctrl:1
	s_nop 1
	v_add_f32_dpp v33, v33, v33 quad_perm:[2,3,0,1] row_mask:0xf bank_mask:0xf bound_ctrl:1
	s_nop 1
	v_add_f32_dpp v33, v33, v33 row_half_mirror row_mask:0xf bank_mask:0xf bound_ctrl:1
	s_nop 1
	v_add_f32_dpp v33, v33, v33 row_mirror row_mask:0xf bank_mask:0xf bound_ctrl:1
	s_nop 0
	v_readlane_b32 s8, v33, 16
	v_readlane_b32 s9, v33, 48
	v_readlane_b32 s0, v33, 0
	v_readlane_b32 s1, v33, 32
	v_mov_b32_e32 v92, s8
	v_mov_b32_e32 v93, s9
	v_pk_add_f32 v[92:93], s[0:1], v[92:93]
	s_nop 0
	v_add_f32_e32 v33, v92, v93
	v_fmac_f32_e32 v76, 0xba800000, v33
	v_fmac_f32_e32 v77, 0xba800000, v33
	v_fmac_f32_e32 v85, 0xba800000, v33
	v_fmac_f32_e32 v84, 0xba800000, v33
	v_mov_b32_e32 v92, v85
	v_mov_b32_e32 v93, v77
	v_mov_b32_e32 v85, v76
	v_pk_mul_f32 v[96:97], v[92:93], v[92:93]
	v_pk_mul_f32 v[76:77], v[84:85], v[84:85]
	v_fmac_f32_e32 v74, 0xba800000, v33
	v_fmac_f32_e32 v75, 0xba800000, v33
	v_fmac_f32_e32 v91, 0xba800000, v33
	v_pk_mov_b32 v[98:99], v[76:77], v[96:97] op_sel:[1,0]
	v_mov_b32_e32 v77, v97
	v_fmac_f32_e32 v90, 0xba800000, v33
	v_mov_b32_e32 v96, v91
	v_mov_b32_e32 v97, v75
	v_mov_b32_e32 v91, v74
	v_pk_add_f32 v[76:77], v[98:99], v[76:77]
	v_pk_mul_f32 v[98:99], v[96:97], v[96:97]
	v_pk_mul_f32 v[74:75], v[90:91], v[90:91]
	v_fmac_f32_e32 v54, 0xba800000, v33
	v_pk_mov_b32 v[100:101], v[74:75], v[98:99] op_sel:[1,0]
	v_mov_b32_e32 v75, v99
	v_fmac_f32_e32 v55, 0xba800000, v33
	v_fmac_f32_e32 v56, 0xba800000, v33
	v_mul_f32_e32 v46, v54, v54
	v_pk_add_f32 v[74:75], v[100:101], v[74:75]
	v_fmac_f32_e32 v57, 0xba800000, v33
	v_pk_fma_f32 v[98:99], v[54:55], v[54:55], v[46:47] op_sel_hi:[1,1,0]
	v_mul_f32_e32 v46, v56, v56
	v_pk_add_f32 v[76:77], v[76:77], v[76:77] op_sel_hi:[0,1]
	v_pk_add_f32 v[74:75], v[74:75], v[74:75] op_sel_hi:[0,1]
	v_pk_fma_f32 v[100:101], v[56:57], v[56:57], v[46:47] op_sel_hi:[1,1,0]
	v_fmac_f32_e32 v47, 0xba800000, v33
	v_fmac_f32_e32 v51, 0xba800000, v33
	v_fmac_f32_e32 v49, 0xba800000, v33
	v_fmac_f32_e32 v53, 0xba800000, v33
	v_mul_f32_e32 v98, v53, v53
	v_mul_f32_e32 v100, v49, v49
	v_mul_f32_e32 v76, v51, v51
	v_mul_f32_e32 v74, v47, v47
	v_pk_add_f32 v[98:99], v[98:99], v[100:101]
	v_pk_add_f32 v[74:75], v[76:77], v[74:75]
	v_mov_b32_e32 v77, v80
	v_pk_add_f32 v[74:75], v[98:99], v[74:75]
	s_nop 0
	v_add_f32_e32 v33, v74, v75
	s_nop 1
; DI unsigned pk2(float lo, float hi) { return f2bf(lo) | (f2bf(hi) << 16); }
; DI float wave_sum(float v) { v = row16_sum(v); return (rdlane(v, 0) + rdlane(v, 16)) + (rdlane(v, 32) + rdlane(v, 48)); }
; DI void phase_ln(const bf16_t* vin, float* xf, bf16_t* xb, const float* g, const float* b, bool write_f32) {
;     ...
;             const float rstd = rsqrtf(wave_sum(q) * (1.0f / 1024.0f) + 1e-5f);
;             float* row = xf + (size_t)(r0 + k * nw) * D_;
;             bf16_t* rb = xb + (size_t)(r0 + k * nw) * D_;
; #pragma unroll
;             for (int i = 0; i < 4; ++i) {
;                 const f32x4 o = (v[k][i] - mean) * rstd * gv[i] + bv[i];
;                 if (write_f32) *(f32x4*)(row + i * 256 + lane * 4) = o;
;                 u32x2 w; w.x = pk2(o[0], o[1]); w.y = pk2(o[2], o[3]);
;                 *(u32x2*)(rb + i * 256 + lane * 4) = w;
;             }
;         }
	v_add_f32_dpp v33, v33, v33 quad_perm:[1,0,3,2] row_mask:0xf bank_mask:0xf bound_ctrl:1
	s_nop 1
	v_add_f32_dpp v33, v33, v33 quad_perm:[2,3,0,1] row_mask:0xf bank_mask:0xf bound_ctrl:1
	s_nop 1
	v_add_f32_dpp v33, v33, v33 row_half_mirror row_mask:0xf bank_mask:0xf bound_ctrl:1
	s_nop 1
	v_add_f32_dpp v33, v33, v33 row_mirror row_mask:0xf bank_mask:0xf bound_ctrl:1
	s_nop 0
	v_readlane_b32 s8, v33, 16
	v_readlane_b32 s9, v33, 48
	v_readlane_b32 s0, v33, 0
	v_readlane_b32 s1, v33, 32
	v_mov_b32_e32 v74, s8
	v_mov_b32_e32 v75, s9
	v_pk_add_f32 v[74:75], s[0:1], v[74:75]
	s_nop 0
	v_mov_b32_e32 v76, v74
	v_mov_b32_e32 v80, v75
	v_pk_add_f32 v[74:75], v[76:77], v[80:81]
	s_nop 0
	v_pk_fma_f32 v[74:75], v[74:75], s[18:19], v[94:95] op_sel_hi:[1,0,0]
	s_nop 0
	v_mul_f32_e32 v33, 0x4b800000, v75
	v_cmp_gt_f32_e64 s[0:1], s44, v75
	s_nop 0
	s_nop 0
	v_cndmask_b32_e64 v33, v75, v33, s[0:1]
	v_rsq_f32_e32 v33, v33
	s_nop 0
	v_mul_f32_e32 v46, 0x45800000, v33
	v_cndmask_b32_e64 v46, v33, v46, s[0:1]
	v_pk_mul_f32 v[76:77], v[78:79], v[46:47] op_sel_hi:[1,0]
	v_pk_mul_f32 v[78:79], v[86:87], v[46:47] op_sel_hi:[1,0]
	v_pk_fma_f32 v[76:77], v[0:1], v[76:77], v[8:9]
	v_pk_fma_f32 v[78:79], v[2:3], v[78:79], v[10:11]
	v_cvt_pk_bf16_f32 v76, v76, v77
	s_nop 0
	s_nop 0
	s_nop 0
	v_cvt_pk_bf16_f32 v77, v78, v79
	global_store_dwordx2 v[72:73], v[76:77], off
	v_pk_mul_f32 v[76:77], v[82:83], v[46:47] op_sel_hi:[1,0]
	v_pk_mul_f32 v[78:79], v[88:89], v[46:47] op_sel_hi:[1,0]
	v_pk_fma_f32 v[76:77], v[4:5], v[76:77], v[12:13]
	v_pk_fma_f32 v[78:79], v[6:7], v[78:79], v[14:15]
	v_cvt_pk_bf16_f32 v76, v76, v77
	v_pk_mul_f32 v[68:69], v[68:69], v[46:47] op_sel_hi:[1,0]
	v_pk_fma_f32 v[68:69], v[16:17], v[68:69], v[24:25]
	v_cvt_pk_bf16_f32 v77, v78, v79
	v_pk_mul_f32 v[70:71], v[70:71], v[46:47] op_sel_hi:[1,0]
	v_pk_fma_f32 v[70:71], v[18:19], v[70:71], v[26:27]
	v_cvt_pk_bf16_f32 v68, v68, v69
	v_pk_mul_f32 v[62:63], v[62:63], v[46:47] op_sel_hi:[1,0]
	v_pk_fma_f32 v[62:63], v[20:21], v[62:63], v[28:29]
	v_cvt_pk_bf16_f32 v69, v70, v71
	v_pk_mul_f32 v[60:61], v[60:61], v[46:47] op_sel_hi:[1,0]
	v_pk_fma_f32 v[60:61], v[22:23], v[60:61], v[30:31]
	v_cvt_pk_bf16_f32 v62, v62, v63
	s_nop 0
	s_nop 0
	v_cvt_pk_bf16_f32 v63, v60, v61
	s_nop 0
	v_mov_b32_e32 v33, v74
	v_rsq_f32_e32 v33, v33
	global_store_dwordx2 v[72:73], v[62:63], off offset:1536
	v_mov_b32_e32 v48, v53
	s_mov_b32 s0, 0xffff
	s_nop 0
	v_mov_b32_e32 v50, v33
	v_pk_mul_f32 v[60:61], v[84:85], v[50:51] op_sel_hi:[1,0]
	v_pk_mul_f32 v[62:63], v[92:93], v[50:51] op_sel_hi:[1,0]
	v_pk_fma_f32 v[60:61], v[0:1], v[60:61], v[8:9]
	v_pk_fma_f32 v[62:63], v[2:3], v[62:63], v[10:11]
	v_cvt_pk_bf16_f32 v60, v60, v61
	s_nop 0
	s_nop 0
	s_nop 0
	v_cvt_pk_bf16_f32 v61, v62, v63
	global_store_dwordx2 v[58:59], v[60:61], off
	v_pk_mul_f32 v[60:61], v[90:91], v[50:51] op_sel_hi:[1,0]
	v_pk_mul_f32 v[62:63], v[96:97], v[50:51] op_sel_hi:[1,0]
	v_pk_fma_f32 v[60:61], v[4:5], v[60:61], v[12:13]
	v_pk_fma_f32 v[62:63], v[6:7], v[62:63], v[14:15]
	v_cvt_pk_bf16_f32 v60, v60, v61
	v_pk_mul_f32 v[54:55], v[54:55], v[50:51] op_sel_hi:[1,0]
	v_pk_fma_f32 v[54:55], v[16:17], v[54:55], v[24:25]
	v_cvt_pk_bf16_f32 v61, v62, v63
	v_pk_mul_f32 v[56:57], v[56:57], v[50:51] op_sel_hi:[1,0]
	v_pk_fma_f32 v[56:57], v[18:19], v[56:57], v[26:27]
	v_cvt_pk_bf16_f32 v54, v54, v55
	v_pk_mul_f32 v[48:49], v[48:49], v[50:51] op_sel_hi:[1,0]
	v_pk_fma_f32 v[48:49], v[20:21], v[48:49], v[28:29]
	v_cvt_pk_bf16_f32 v55, v56, v57
	v_mov_b32_e32 v46, v51
	v_pk_mul_f32 v[46:47], v[46:47], v[50:51] op_sel_hi:[1,0]
	v_pk_fma_f32 v[46:47], v[22:23], v[46:47], v[30:31]
	v_cvt_pk_bf16_f32 v48, v48, v49
	v_cvt_pk_bf16_f32 v33, v46, v46
	s_nop 0
	v_lshrrev_b32_e32 v33, 16, v33
	v_cvt_pk_bf16_f32 v46, v47, v47
	v_cmp_lt_i32_e32 vcc, s0, v32
	v_and_or_b32 v49, v46, s39, v33
	s_or_b64 s[6:7], vcc, s[6:7]
	global_store_dwordx2 v[72:73], v[76:77], off offset:512
	global_store_dwordx2 v[72:73], v[68:69], off offset:1024
	global_store_dwordx2 v[58:59], v[60:61], off offset:512
	global_store_dwordx2 v[58:59], v[54:55], off offset:1024
	global_store_dwordx2 v[58:59], v[48:49], off offset:1536
	s_andn2_b64 exec, exec, s[6:7]
	s_cbranch_execnz .LBB0_568
